# prep streaming loop: resident rmsnorm gains, weight-block gains by scalar loads, counted waits so the next item's loads stay in flight behind the current item
# speedup vs baseline: 1.0156x; 1.0035x over previous
; __device__ __forceinline__ void item_load(const Params& p, int it, f32x4 (&v)[8]) {
;     const int tid = otid(); WDesc d;
;     if (item_desc(p, it, d)) {
; #pragma unroll
;         for (int i = 0; i < 8; ++i) { const int idx = tid + i * 512, row = idx >> 6, c4 = idx & 63;
;             v[i] = __builtin_nontemporal_load((const f32x4*)(d.W + (size_t)(d.kb * 64 + row) * d.N + d.nb * 256 + c4 * 4)); }
;     } else {
;         const int R = it - PO_NORM, wid = tid >> 6, lane = tid & 63;
; #pragma unroll
;         for (int q = 0; q < 2; ++q)
; #pragma unroll
;             for (int i = 0; i < 4; ++i) v[q * 4 + i] = __builtin_nontemporal_load((const f32x4*)(p.x + ((size_t)R * 16 + wid * 2 + q) * DM + i * 256 + lane * 4));
;     }
; __device__ __forceinline__ void item_finish(const Params& p, int it, const f32x4 (&v)[8], LAS unsigned char* lds) {
;     ...
;         for (int i = 0; i < 4; ++i) { const int idx = tid + i * 512, col = idx >> 3, piece = idx & 7; float t[8];
; #pragma unroll
;             for (int k = 0; k < 8; ++k) t[k] = tile[(piece * 8 + k) * 257 + col];
;             u32x4 w4; w4.x = cvt_pk_bf16(t[0], t[1]); w4.y = cvt_pk_bf16(t[2], t[3]); w4.z = cvt_pk_bf16(t[4], t[5]); w4.w = cvt_pk_bf16(t[6], t[7]);
;             *(u32x4*)(d.Bt + (size_t)dest_row(d.kind, d.nb * 256 + col, d.NPART) * d.K + d.kb * 64 + piece * 8) = w4; }
;         __syncthreads();
;     } else {
;         const int R = it - PO_NORM, wid = tid >> 6, lane = tid & 63; bf16_t* AP = (bf16_t*)(p.ws + WS_AP);
; #pragma unroll
;         for (int q = 0; q < 2; ++q) { const int s = wid * 2 + q; float ss = 0.f;
; #pragma unroll
;             for (int i = 0; i < 4; ++i) { const f32x4 x = v[q * 4 + i]; ss += (x[0] * x[0] + x[1] * x[1]) + (x[2] * x[2] + x[3] * x[3]); }
; #pragma unroll
;             for (int o = 32; o >= 1; o >>= 1) ss += __shfl_xor(ss, o);
;             const float rs = rsqrtf(ss * (1.0f / DM) + RMS_EPS);
; #pragma unroll
;             for (int i = 0; i < 4; ++i) { const int c = i * 256 + lane * 4; const f32x4 gn = *(const f32x4*)(p.norm_mix + c); const f32x4 x = v[q * 4 + i];
;                 u32x2 w; w.x = cvt_pk_bf16(x[0] * rs * gn[0], x[1] * rs * gn[1]); w.y = cvt_pk_bf16(x[2] * rs * gn[2], x[3] * rs * gn[3]);
;                 *(u32x2*)(AP + ((size_t)(c >> 4) * NROW + R) * KA + s * 16 + (c & 15)) = w; } }
;     }
; }
.LBB0_129:
	global_load_dwordx4 v[62:65], v[30:31], off nt
	s_add_u32 s4, s94, 0xb00000
	s_addc_u32 s5, s95, 0
	s_add_u32 s6, s88, 0x1600000
	s_addc_u32 s7, s89, 0
	s_add_u32 s10, s62, 0x2d84000
	s_addc_u32 s11, s63, 0
	s_add_u32 s64, s62, 0x2584000
	v_readlane_b32 s36, v252, 6
	s_addc_u32 s65, s63, 0
	v_readlane_b32 s38, v252, 8
	v_readlane_b32 s39, v252, 9
	s_add_u32 s66, s38, 0x1000
	s_addc_u32 s67, s39, 0
	s_add_u32 s70, s62, 0x2004000
	s_addc_u32 s71, s63, 0
	s_add_u32 s22, s62, 0x1a84000
	s_addc_u32 s23, s63, 0
	s_add_u32 s24, s62, 0xf84000
	v_readlane_b32 s40, v252, 10
	s_addc_u32 s25, s63, 0
	v_readlane_b32 s41, v252, 11
	s_add_u32 s26, s40, 0x1000
	s_addc_u32 s27, s41, 0
	s_add_u32 s28, s62, 0x484000
	s_addc_u32 s29, s63, 0
	s_add_u32 s30, s62, 0x84000
	v_mbcnt_lo_u32_b32 v30, -1, 0
	s_addc_u32 s31, s63, 0
	s_mov_b32 s53, 0
	v_mov_b32_e32 v67, 0
	v_mov_b32_e32 v1, 0x358637bd
	s_mov_b32 s8, 0x800000
	s_movk_i32 s9, 0x300
	s_mov_b32 s12, 0x17800
	s_mov_b32 s13, 0x1f800
	s_movk_i32 s14, 0x404
	s_movk_i32 s15, 0x60
	v_mbcnt_hi_u32_b32 v72, -1, v30
	v_mov_b32_e32 v73, 0x8000
	v_mov_b32_e32 v74, 0x10000
	v_mov_b32_e32 v75, 0x18000
	s_mov_b32 s33, s20
	v_readlane_b32 s37, v252, 7
	v_readlane_b32 s42, v252, 12
	v_readlane_b32 s43, v252, 13
	v_readlane_b32 s44, v252, 14
	v_readlane_b32 s45, v252, 15
	v_readlane_b32 s46, v252, 16
	v_readlane_b32 s47, v252, 17
	v_readlane_b32 s48, v252, 18
	v_readlane_b32 s49, v252, 19
	v_readlane_b32 s50, v252, 20
	v_readlane_b32 s51, v252, 21
	v_lshlrev_b32_e32 v122, 2, v232
	v_and_b32_e32 v122, 0xfc, v122
	v_lshlrev_b32_e32 v122, 2, v122
	v_readlane_b32 s74, v252, 8
	v_readlane_b32 s75, v252, 9
	s_nop 4
	global_load_dwordx4 v[106:109], v122, s[74:75]
	global_load_dwordx4 v[110:113], v122, s[74:75] offset:1024
	global_load_dwordx4 v[114:117], v122, s[74:75] offset:2048
	global_load_dwordx4 v[118:121], v122, s[74:75] offset:3072
	s_waitcnt vmcnt(0)
	s_branch .LBB0_132
.LBB0_130:
	v_ashrrev_i32_e32 v8, 31, v11
	v_mul_lo_u32 v10, s85, v11
	v_mul_lo_u32 v12, s84, v8
	v_mad_u64_u32 v[8:9], s[0:1], s84, v11, 0
	v_add3_u32 v9, v9, v12, v10
	v_lshl_add_u64 v[6:7], v[8:9], 1, v[6:7]
	global_store_dwordx4 v[6:7], v[2:5], off
	s_barrier
	s_waitcnt vmcnt(4)
	s_branch .Lprep1_copy

; __device__ __forceinline__ void run_items(const Params& p, int it0, int step, int end, LAS unsigned char* lds) {
;     ...
;         if (more) {
; #pragma unroll
;             for (int i = 0; i < 8; ++i) cur[i] = nxt[i]; }
.Lprep1_copy:
	s_add_i32 s33, s33, s2
	s_cmp_lt_i32 s33, s3
	v_mov_b32_e32 v26, v58
	v_mov_b32_e32 v27, v59
	v_mov_b32_e32 v28, v60
	v_mov_b32_e32 v29, v61
	v_mov_b32_e32 v22, v54
	v_mov_b32_e32 v23, v55
	v_mov_b32_e32 v24, v56
	v_mov_b32_e32 v25, v57
	v_mov_b32_e32 v18, v50
	v_mov_b32_e32 v19, v51
	v_mov_b32_e32 v20, v52
	v_mov_b32_e32 v21, v53
	v_mov_b32_e32 v14, v46
	v_mov_b32_e32 v15, v47
	v_mov_b32_e32 v16, v48
	v_mov_b32_e32 v17, v49
	v_mov_b32_e32 v10, v42
	v_mov_b32_e32 v11, v43
	v_mov_b32_e32 v12, v44
	v_mov_b32_e32 v13, v45
	v_mov_b32_e32 v6, v38
	v_mov_b32_e32 v7, v39
	v_mov_b32_e32 v8, v40
	v_mov_b32_e32 v9, v41
	v_mov_b32_e32 v2, v34
	v_mov_b32_e32 v3, v35
	v_mov_b32_e32 v4, v36
	v_mov_b32_e32 v5, v37
	v_mov_b32_e32 v62, v30
	v_mov_b32_e32 v63, v31
	v_mov_b32_e32 v64, v32
	v_mov_b32_e32 v65, v33
	s_cbranch_scc0 .LBB0_237

; __device__ __forceinline__ void item_finish(const Params& p, int it, const f32x4 (&v)[8], LAS unsigned char* lds) {
;     ...
;         const int R = it - PO_NORM, wid = tid >> 6, lane = tid & 63; bf16_t* AP = (bf16_t*)(p.ws + WS_AP);
; #pragma unroll
;         for (int q = 0; q < 2; ++q) { const int s = wid * 2 + q; float ss = 0.f;
; #pragma unroll
;             for (int i = 0; i < 4; ++i) { const f32x4 x = v[q * 4 + i]; ss += (x[0] * x[0] + x[1] * x[1]) + (x[2] * x[2] + x[3] * x[3]); }
; #pragma unroll
;             for (int o = 32; o >= 1; o >>= 1) ss += __shfl_xor(ss, o);
;             const float rs = rsqrtf(ss * (1.0f / DM) + RMS_EPS);
.LBB0_163:
	v_mov_b32_e32 v68, v232
	s_mov_b64 s[0:1], -1
	s_cmpk_gt_i32 s33, 0x5df
	v_lshlrev_b32_e32 v69, 3, v68
	s_cbranch_scc0 .LBB0_165
	v_lshlrev_b32_e32 v66, 2, v68
	v_and_b32_e32 v90, 0xfc, v66
	v_readlane_b32 s72, v252, 6
	v_lshlrev_b32_e32 v98, 2, v90
	v_readlane_b32 s74, v252, 8
	v_readlane_b32 s75, v252, 9
	v_pk_mul_f32 v[70:71], v[24:25], v[24:25]
	v_pk_mul_f32 v[80:81], v[22:23], v[22:23]
	v_pk_mul_f32 v[82:83], v[28:29], v[28:29]
	v_pk_mul_f32 v[84:85], v[26:27], v[26:27]
	v_and_b32_e32 v87, 64, v72
	s_nop 0
	v_pk_mov_b32 v[88:89], v[84:85], v[82:83] op_sel:[1,0]
	v_mov_b32_e32 v85, v83
	v_pk_mov_b32 v[82:83], v[80:81], v[70:71] op_sel:[1,0]
	v_mov_b32_e32 v81, v71
	v_mul_f32_e32 v66, v18, v18
	v_mul_f32_e32 v86, v20, v20
	v_pk_add_f32 v[84:85], v[88:89], v[84:85]
	v_pk_add_f32 v[80:81], v[82:83], v[80:81]
	v_add_u32_e32 v92, 64, v87
	v_pk_fma_f32 v[70:71], v[18:19], v[18:19], v[66:67] op_sel_hi:[1,1,0]
	v_pk_fma_f32 v[86:87], v[20:21], v[20:21], v[86:87] op_sel_hi:[1,1,0]
	v_pk_add_f32 v[82:83], v[84:85], v[84:85] op_sel_hi:[0,1]
	v_pk_add_f32 v[80:81], v[80:81], v[80:81] op_sel_hi:[0,1]
	v_xor_b32_e32 v91, 32, v72
	v_mul_f32_e32 v70, v14, v14
	v_mul_f32_e32 v86, v15, v15
	v_mul_f32_e32 v82, v16, v16
	v_mul_f32_e32 v80, v17, v17
	v_cmp_lt_i32_e32 vcc, v91, v92
	v_pk_add_f32 v[70:71], v[70:71], v[86:87]
	v_pk_add_f32 v[80:81], v[82:83], v[80:81]
	v_cndmask_b32_e32 v66, v72, v91, vcc
	v_pk_add_f32 v[70:71], v[70:71], v[80:81]
	v_lshlrev_b32_e32 v99, 2, v66
	v_add_f32_e32 v66, v70, v71
	ds_bpermute_b32 v70, v99, v66
	v_xor_b32_e32 v71, 16, v72
	v_cmp_lt_i32_e32 vcc, v71, v92
	v_ashrrev_i32_e32 v82, 1, v68
	v_lshlrev_b32_e32 v86, 7, v90
	v_cndmask_b32_e32 v71, v72, v71, vcc
	v_lshlrev_b32_e32 v100, 2, v71
	s_waitcnt lgkmcnt(0)
	v_add_f32_e32 v66, v66, v70
	ds_bpermute_b32 v70, v100, v66
	v_xor_b32_e32 v71, 8, v72
	v_cmp_lt_i32_e32 vcc, v71, v92
	s_add_i32 s16, s33, 0xfffffa20
	v_mul_f32_e32 v94, v4, v4
	v_cndmask_b32_e32 v71, v72, v71, vcc
	v_lshlrev_b32_e32 v101, 2, v71
	s_waitcnt lgkmcnt(0)
	v_add_f32_e32 v66, v66, v70
	ds_bpermute_b32 v70, v101, v66
	v_xor_b32_e32 v71, 4, v72
	v_cmp_lt_i32_e32 vcc, v71, v92
	v_pk_fma_f32 v[94:95], v[4:5], v[4:5], v[94:95] op_sel_hi:[1,1,0]
	v_readlane_b32 s73, v252, 7
	v_cndmask_b32_e32 v71, v72, v71, vcc
	v_lshlrev_b32_e32 v102, 2, v71
	s_waitcnt lgkmcnt(0)
	v_add_f32_e32 v66, v66, v70
	ds_bpermute_b32 v70, v102, v66
	v_xor_b32_e32 v71, 2, v72
	v_cmp_lt_i32_e32 vcc, v71, v92
	v_mul_f32_e32 v94, v63, v63
	v_readlane_b32 s76, v252, 10
	v_cndmask_b32_e32 v71, v72, v71, vcc
	v_lshlrev_b32_e32 v103, 2, v71
	s_waitcnt lgkmcnt(0)
	v_add_f32_e32 v66, v66, v70
	ds_bpermute_b32 v70, v103, v66
	v_xor_b32_e32 v71, 1, v72
	v_cmp_lt_i32_e32 vcc, v71, v92
	v_pk_mul_f32 v[92:93], v[10:11], v[10:11]
	v_readlane_b32 s77, v252, 11
	v_cndmask_b32_e32 v71, v72, v71, vcc
	v_lshlrev_b32_e32 v104, 2, v71
	s_waitcnt lgkmcnt(0)
	v_add_f32_e32 v80, v66, v70
	ds_bpermute_b32 v81, v104, v80
	v_and_b32_e32 v66, 24, v69
	v_lshl_add_u64 v[70:71], s[96:97], 0, v[66:67]
	v_readlane_b32 s78, v252, 12
	v_readlane_b32 s79, v252, 13
	s_waitcnt lgkmcnt(0)
; __device__ __forceinline__ unsigned cvt_pk_bf16(float lo, float hi) { unsigned r; asm volatile("v_cvt_pk_bf16_f32 %0, %1, %2" : "=v"(r) : "v"(lo), "v"(hi)); return r; }
; __device__ __forceinline__ void item_finish(const Params& p, int it, const f32x4 (&v)[8], LAS unsigned char* lds) {
;     ...
;             const float rs = rsqrtf(ss * (1.0f / DM) + RMS_EPS);
; #pragma unroll
;             for (int i = 0; i < 4; ++i) { const int c = i * 256 + lane * 4; const f32x4 gn = *(const f32x4*)(p.norm_mix + c); const f32x4 x = v[q * 4 + i];
;                 u32x2 w; w.x = cvt_pk_bf16(x[0] * rs * gn[0], x[1] * rs * gn[1]); w.y = cvt_pk_bf16(x[2] * rs * gn[2], x[3] * rs * gn[3]);
;                 *(u32x2*)(AP + ((size_t)(c >> 4) * NROW + R) * KA + s * 16 + (c & 15)) = w; } }
	v_add_f32_e32 v66, v80, v81
	v_fmamk_f32 v66, v66, 0x3a800000, v1
	v_mul_f32_e32 v80, 0x4b800000, v66
	v_cmp_gt_f32_e32 vcc, s8, v66
	v_readlane_b32 s80, v252, 14
	v_readlane_b32 s81, v252, 15
	v_cndmask_b32_e32 v66, v66, v80, vcc
	v_rsq_f32_e32 v66, v66
	v_and_b32_e32 v80, 0xffffffe0, v82
	v_ashrrev_i32_e32 v81, 31, v80
	v_lshl_add_u64 v[70:71], v[80:81], 1, v[70:71]
	v_mul_f32_e32 v80, 0x45800000, v66
	v_cndmask_b32_e32 v66, v66, v80, vcc
	v_mul_f32_e32 v80, v26, v66
	v_mul_f32_e32 v81, v27, v66
	v_mul_f32_e32 v76, v106, v80
	v_mul_f32_e32 v77, v107, v81
	v_cvt_pk_bf16_f32 v76, v76, v77
	v_mul_f32_e32 v77, v28, v66
	v_mul_f32_e32 v77, v108, v77
	v_mul_f32_e32 v78, v29, v66
	v_mul_f32_e32 v78, v109, v78
	v_cvt_pk_bf16_f32 v77, v77, v78
	v_and_b32_e32 v78, 0x7800, v86
	v_add_u32_e32 v78, s16, v78
	v_mad_u64_u32 v[80:81], s[0:1], v78, s9, v[70:71]
	global_store_dwordx2 v[80:81], v[76:77], off
	s_nop 0
	s_mov_b32 s0, 0xf800
	v_bitop3_b32 v82, v86, s0, v73 bitop3:0xc8
	v_add_u32_e32 v82, s16, v82
	v_mul_f32_e32 v84, v22, v66
	v_mul_f32_e32 v85, v23, v66
	v_mad_u64_u32 v[82:83], s[0:1], v82, s9, v[70:71]
	v_mul_f32_e32 v87, v24, v66
	v_mul_f32_e32 v88, v25, v66
	v_mul_f32_e32 v89, v20, v66
	v_mul_f32_e32 v90, v21, v66
	v_readlane_b32 s82, v252, 16
	v_readlane_b32 s83, v252, 17
	v_readlane_b32 s84, v252, 18
	v_readlane_b32 s85, v252, 19
	v_readlane_b32 s86, v252, 20
	v_readlane_b32 s87, v252, 21
	v_mul_f32_e32 v76, v110, v84
	v_mul_f32_e32 v77, v111, v85
	v_mul_f32_e32 v78, v112, v87
	v_mul_f32_e32 v79, v113, v88
	v_cvt_pk_bf16_f32 v76, v76, v77
	v_cvt_pk_bf16_f32 v77, v78, v79
	global_store_dwordx2 v[82:83], v[76:77], off
	s_nop 0
	v_bitop3_b32 v84, v86, s12, v74 bitop3:0xc8
	v_add_u32_e32 v84, s16, v84
	v_mul_f32_e32 v87, v18, v66
	v_mul_f32_e32 v88, v19, v66
	v_mad_u64_u32 v[84:85], s[0:1], v84, s9, v[70:71]
	v_bitop3_b32 v86, v86, s13, v75 bitop3:0xc8
	v_add_u32_e32 v86, s16, v86
	v_mad_u64_u32 v[70:71], s[0:1], v86, s9, v[70:71]
	v_mul_f32_e32 v86, v14, v66
	s_mov_b64 s[0:1], 0
	v_mul_f32_e32 v76, v87, v114
	v_mul_f32_e32 v77, v88, v115
	v_mul_f32_e32 v78, v89, v116
	v_mul_f32_e32 v79, v90, v117
	v_cvt_pk_bf16_f32 v76, v76, v77
	v_cvt_pk_bf16_f32 v77, v78, v79
	global_store_dwordx2 v[84:85], v[76:77], off
	s_nop 0
	v_mul_f32_e32 v87, v15, v66
	v_mul_f32_e32 v88, v16, v66
	v_mul_f32_e32 v66, v17, v66
	v_pk_mul_f32 v[90:91], v[12:13], v[12:13]
	v_mul_f32_e32 v76, v86, v118
	v_mul_f32_e32 v77, v87, v119
	v_mul_f32_e32 v78, v88, v120
	v_mul_f32_e32 v66, v66, v121
	v_cvt_pk_bf16_f32 v76, v76, v77
	v_cvt_pk_bf16_f32 v77, v78, v66
	global_store_dwordx2 v[70:71], v[76:77], off
	s_nop 0
	v_pk_mul_f32 v[86:87], v[8:9], v[8:9]
	v_pk_mul_f32 v[88:89], v[6:7], v[6:7]
	v_pk_mov_b32 v[96:97], v[92:93], v[90:91] op_sel:[1,0]
	v_mov_b32_e32 v93, v91
	v_pk_mov_b32 v[90:91], v[88:89], v[86:87] op_sel:[1,0]
	v_mov_b32_e32 v89, v87
	v_mul_f32_e32 v66, v2, v2
	v_pk_add_f32 v[92:93], v[96:97], v[92:93]
	v_pk_add_f32 v[88:89], v[90:91], v[88:89]
	v_pk_fma_f32 v[86:87], v[2:3], v[2:3], v[66:67] op_sel_hi:[1,1,0]
	v_pk_add_f32 v[90:91], v[92:93], v[92:93] op_sel_hi:[0,1]
	v_pk_add_f32 v[88:89], v[88:89], v[88:89] op_sel_hi:[0,1]
	v_mul_f32_e32 v86, v62, v62
	v_mul_f32_e32 v90, v64, v64
	v_mul_f32_e32 v88, v65, v65
	v_pk_add_f32 v[86:87], v[86:87], v[94:95]
	v_pk_add_f32 v[88:89], v[90:91], v[88:89]
	s_nop 0
	v_pk_add_f32 v[86:87], v[86:87], v[88:89]
	s_nop 0
	v_add_f32_e32 v66, v86, v87
	ds_bpermute_b32 v86, v99, v66
	s_waitcnt lgkmcnt(0)
	v_add_f32_e32 v66, v66, v86
	ds_bpermute_b32 v86, v100, v66
	s_waitcnt lgkmcnt(0)
	v_add_f32_e32 v66, v66, v86
	ds_bpermute_b32 v86, v101, v66
	s_waitcnt lgkmcnt(0)
	v_add_f32_e32 v66, v66, v86
	ds_bpermute_b32 v86, v102, v66
	s_waitcnt lgkmcnt(0)
	v_add_f32_e32 v66, v66, v86
	ds_bpermute_b32 v86, v103, v66
	s_waitcnt lgkmcnt(0)
	v_add_f32_e32 v66, v66, v86
	ds_bpermute_b32 v86, v104, v66
	s_waitcnt lgkmcnt(0)
	v_add_f32_e32 v66, v66, v86
	v_fmamk_f32 v66, v66, 0x3a800000, v1
	v_mul_f32_e32 v86, 0x4b800000, v66
	v_cmp_gt_f32_e32 vcc, s8, v66
	s_nop 1
	v_cndmask_b32_e32 v66, v66, v86, vcc
	v_rsq_f32_e32 v66, v66
	s_nop 0
	v_mul_f32_e32 v86, 0x45800000, v66
	v_cndmask_b32_e32 v66, v66, v86, vcc
	v_mul_f32_e32 v86, v10, v66
	v_mul_f32_e32 v87, v11, v66
	v_mul_f32_e32 v88, v12, v66
	v_mul_f32_e32 v89, v13, v66
	v_mul_f32_e32 v76, v106, v86
	v_mul_f32_e32 v77, v107, v87
	v_mul_f32_e32 v78, v108, v88
	v_mul_f32_e32 v79, v109, v89
	v_cvt_pk_bf16_f32 v76, v76, v77
	v_cvt_pk_bf16_f32 v77, v78, v79
	global_store_dwordx2 v[80:81], v[76:77], off offset:32
	s_nop 0
	v_mul_f32_e32 v80, v6, v66
	v_mul_f32_e32 v81, v7, v66
	v_mul_f32_e32 v86, v8, v66
	v_mul_f32_e32 v87, v9, v66
	v_mul_f32_e32 v76, v110, v80
	v_mul_f32_e32 v77, v111, v81
	v_mul_f32_e32 v78, v112, v86
	v_mul_f32_e32 v79, v113, v87
	v_cvt_pk_bf16_f32 v76, v76, v77
	v_cvt_pk_bf16_f32 v77, v78, v79
	global_store_dwordx2 v[82:83], v[76:77], off offset:32
	s_nop 0
	v_mul_f32_e32 v80, v2, v66
	v_mul_f32_e32 v81, v3, v66
	v_mul_f32_e32 v82, v4, v66
	v_mul_f32_e32 v83, v5, v66
	v_mul_f32_e32 v76, v80, v114
	v_mul_f32_e32 v77, v81, v115
	v_mul_f32_e32 v78, v82, v116
	v_mul_f32_e32 v79, v83, v117
	v_cvt_pk_bf16_f32 v76, v76, v77
	v_cvt_pk_bf16_f32 v77, v78, v79
	global_store_dwordx2 v[84:85], v[76:77], off offset:32
	s_nop 0
	v_mul_f32_e32 v80, v62, v66
	v_mul_f32_e32 v81, v63, v66
	v_mul_f32_e32 v82, v64, v66
	v_mul_f32_e32 v66, v65, v66
	v_mul_f32_e32 v76, v80, v118
	v_mul_f32_e32 v77, v81, v119
	v_mul_f32_e32 v78, v82, v120
	v_mul_f32_e32 v66, v66, v121
	v_cvt_pk_bf16_f32 v76, v76, v77
	v_cvt_pk_bf16_f32 v77, v78, v66
	global_store_dwordx2 v[70:71], v[76:77], off offset:32
	s_waitcnt vmcnt(8)
	s_branch .Lprep1_copy

; #define LAS __attribute__((address_space(3)))
; __device__ __forceinline__ unsigned cvt_pk_bf16(float lo, float hi) { unsigned r; asm volatile("v_cvt_pk_bf16_f32 %0, %1, %2" : "=v"(r) : "v"(lo), "v"(hi)); return r; }
; __device__ __forceinline__ void item_finish(const Params& p, int it, const f32x4 (&v)[8], LAS unsigned char* lds) {
;     ...
;         LAS float* tile = (LAS float*)lds;
; #pragma unroll
;         for (int i = 0; i < 8; ++i) { const int idx = tid + i * 512, row = idx >> 6, c4 = idx & 63; f32x4 x = v[i];
;             if (d.gain) { const float gk = d.gain[d.kb * 64 + row]; x *= gk; }
;             tile[row * 257 + c4 * 4 + 0] = x[0]; tile[row * 257 + c4 * 4 + 1] = x[1]; tile[row * 257 + c4 * 4 + 2] = x[2]; tile[row * 257 + c4 * 4 + 3] = x[3]; }
;         __syncthreads();
; #pragma unroll
;         for (int i = 0; i < 4; ++i) { const int idx = tid + i * 512, col = idx >> 3, piece = idx & 7; float t[8];
; #pragma unroll
;             for (int k = 0; k < 8; ++k) t[k] = tile[(piece * 8 + k) * 257 + col];
;             u32x4 w4; w4.x = cvt_pk_bf16(t[0], t[1]); w4.y = cvt_pk_bf16(t[2], t[3]); w4.z = cvt_pk_bf16(t[4], t[5]); w4.w = cvt_pk_bf16(t[6], t[7]);
;             *(u32x4*)(d.Bt + (size_t)dest_row(d.kind, d.nb * 256 + col, d.NPART) * d.K + d.kb * 64 + piece * 8) = w4; }
.LBB0_189:
	s_cmp_lg_u64 s[88:89], 0
	s_cselect_b64 s[90:91], -1, 0
	s_lshl_b32 s17, s17, 6
	s_cmp_eq_u64 s[88:89], 0
	v_ashrrev_i32_e32 v70, 6, v68
	s_cbranch_scc1 .LBB0_191
	s_nop 0
	v_readfirstlane_b32 s72, v70
	s_nop 1
	s_add_i32 s72, s72, s17
	s_lshl_b32 s72, s72, 2
	s_add_u32 s80, s88, s72
	s_addc_u32 s81, s89, 0
	s_load_dword s72, s[80:81], 0x0
	s_load_dword s73, s[80:81], 0x20
	s_load_dword s74, s[80:81], 0x40
	s_load_dword s75, s[80:81], 0x60
	s_load_dword s76, s[80:81], 0x80
	s_load_dword s77, s[80:81], 0xa0
	s_load_dword s78, s[80:81], 0xc0
	s_load_dword s79, s[80:81], 0xe0
	s_waitcnt lgkmcnt(0)
	v_mul_f32_e32 v28, s72, v28
	v_mul_f32_e32 v29, s72, v29
	v_mul_f32_e32 v26, s72, v26
	v_mul_f32_e32 v27, s72, v27
.LBB0_191:
	v_lshlrev_b32_e32 v66, 4, v68
	v_and_b32_e32 v66, 0x3f0, v66
	v_add_u32_e32 v66, 0, v66
	v_mad_u64_u32 v[70:71], s[0:1], v70, s14, v[66:67]
	ds_write2_b32 v70, v26, v27 offset1:1
	ds_write2_b32 v70, v28, v29 offset0:2 offset1:3
	v_add_u32_e32 v26, 0x200, v68
	v_cndmask_b32_e64 v27, 0, 1, s[90:91]
	v_cmp_ne_u32_e64 s[0:1], 1, v27
	s_andn2_b64 vcc, exec, s[90:91]
	v_ashrrev_i32_e32 v27, 6, v26
	s_cbranch_vccnz .LBB0_193
	v_mul_f32_e32 v24, s73, v24
	v_mul_f32_e32 v25, s73, v25
	v_mul_f32_e32 v22, s73, v22
	v_mul_f32_e32 v23, s73, v23
.LBB0_193:
	v_mad_u64_u32 v[28:29], s[18:19], v27, s14, v[66:67]
	ds_write2_b32 v28, v22, v23 offset1:1
	ds_write2_b32 v28, v24, v25 offset0:2 offset1:3
	v_add_u32_e32 v22, 0x400, v68
	s_and_b64 vcc, exec, s[0:1]
	v_ashrrev_i32_e32 v23, 6, v22
	s_cbranch_vccnz .LBB0_195
	v_mul_f32_e32 v20, s74, v20
	v_mul_f32_e32 v21, s74, v21
	v_mul_f32_e32 v18, s74, v18
	v_mul_f32_e32 v19, s74, v19
.LBB0_195:
	v_mad_u64_u32 v[24:25], s[18:19], v23, s14, v[66:67]
	ds_write2_b32 v24, v18, v19 offset1:1
	ds_write2_b32 v24, v20, v21 offset0:2 offset1:3
	v_add_u32_e32 v18, 0x600, v68
	s_and_b64 vcc, exec, s[0:1]
	v_ashrrev_i32_e32 v19, 6, v18
	s_cbranch_vccnz .LBB0_197
	v_mul_f32_e32 v16, s75, v16
	v_mul_f32_e32 v17, s75, v17
	v_mul_f32_e32 v14, s75, v14
	v_mul_f32_e32 v15, s75, v15
.LBB0_197:
	v_mad_u64_u32 v[20:21], s[18:19], v19, s14, v[66:67]
	ds_write2_b32 v20, v14, v15 offset1:1
	ds_write2_b32 v20, v16, v17 offset0:2 offset1:3
	v_add_u32_e32 v14, 0x800, v68
	s_and_b64 vcc, exec, s[0:1]
	v_ashrrev_i32_e32 v14, 6, v14
	s_cbranch_vccnz .LBB0_199
	v_mul_f32_e32 v12, s76, v12
	v_mul_f32_e32 v13, s76, v13
	v_mul_f32_e32 v10, s76, v10
	v_mul_f32_e32 v11, s76, v11
.LBB0_199:
	v_mad_u64_u32 v[14:15], s[18:19], v14, s14, v[66:67]
	ds_write2_b32 v14, v10, v11 offset1:1
	ds_write2_b32 v14, v12, v13 offset0:2 offset1:3
	v_add_u32_e32 v10, 0xa00, v68
	s_and_b64 vcc, exec, s[0:1]
	v_ashrrev_i32_e32 v10, 6, v10
	s_cbranch_vccnz .LBB0_201
	v_mul_f32_e32 v8, s77, v8
	v_mul_f32_e32 v9, s77, v9
	v_mul_f32_e32 v6, s77, v6
	v_mul_f32_e32 v7, s77, v7
.LBB0_201:
	v_mad_u64_u32 v[10:11], s[18:19], v10, s14, v[66:67]
	ds_write2_b32 v10, v6, v7 offset1:1
	ds_write2_b32 v10, v8, v9 offset0:2 offset1:3
	v_add_u32_e32 v6, 0xc00, v68
	s_and_b64 vcc, exec, s[0:1]
	v_ashrrev_i32_e32 v6, 6, v6
	s_cbranch_vccnz .LBB0_203
	v_mul_f32_e32 v4, s78, v4
	v_mul_f32_e32 v5, s78, v5
	v_mul_f32_e32 v2, s78, v2
	v_mul_f32_e32 v3, s78, v3
.LBB0_203:
	v_mad_u64_u32 v[6:7], s[18:19], v6, s14, v[66:67]
	ds_write2_b32 v6, v2, v3 offset1:1
	ds_write2_b32 v6, v4, v5 offset0:2 offset1:3
	v_add_u32_e32 v2, 0xe00, v68
	s_and_b64 vcc, exec, s[0:1]
	v_ashrrev_i32_e32 v2, 6, v2
	s_cbranch_vccnz .LBB0_205
	v_mul_f32_e32 v64, s79, v64
	v_mul_f32_e32 v65, s79, v65
	v_mul_f32_e32 v62, s79, v62
	v_mul_f32_e32 v63, s79, v63
.LBB0_205:
	v_and_b32_e32 v6, 56, v69
	v_ashrrev_i32_e32 v9, 3, v68
	v_mad_u64_u32 v[2:3], s[0:1], v2, s14, v[66:67]
	v_lshlrev_b32_e32 v11, 2, v9
	v_mul_u32_u24_e32 v8, 0x404, v6
	ds_write2_b32 v2, v62, v63 offset1:1
	ds_write2_b32 v2, v64, v65 offset0:2 offset1:3
	v_add3_u32 v2, 0, v11, v8
	s_waitcnt lgkmcnt(0)
	s_barrier
	ds_read_b32 v3, v2 offset:1028
	ds_read_b32 v4, v2 offset:2056
	ds_read_b32 v5, v2 offset:7196
	ds_read_b32 v7, v2 offset:5140
	ds_read_b32 v10, v2 offset:3084
	ds_read_b32 v12, v2
	ds_read_b32 v13, v2 offset:4112
	ds_read_b32 v14, v2 offset:6168
	v_readlane_b32 s88, v252, 40
	s_lshl_b32 s16, s16, 8
	v_readlane_b32 s89, v252, 41
	v_readlane_b32 s94, v252, 46
	v_readlane_b32 s95, v252, 47
	s_waitcnt lgkmcnt(2)
	v_cvt_pk_bf16_f32 v2, v12, v3
	v_cvt_pk_bf16_f32 v3, v4, v10
	s_waitcnt lgkmcnt(1)
	v_cvt_pk_bf16_f32 v4, v13, v7
	v_add_u32_e32 v7, s16, v9
	s_cmp_lt_i32 s35, 1
	s_mov_b64 s[0:1], -1
	v_readlane_b32 s90, v252, 42
	v_readlane_b32 s91, v252, 43
	v_readlane_b32 s92, v252, 44
	v_readlane_b32 s93, v252, 45
	s_waitcnt lgkmcnt(0)
	v_cvt_pk_bf16_f32 v5, v14, v5
	s_cbranch_scc1 .LBB0_211
	s_cmp_lg_u32 s35, 1
	s_cbranch_scc0 .LBB0_208
	v_and_b32_e32 v10, 16, v11
	v_lshrrev_b32_e32 v11, 1, v9
	v_and_b32_e32 v11, 12, v11
	v_and_b32_e32 v12, 0xffffffe3, v7
	v_or3_b32 v10, v11, v10, v12
	s_mov_b64 s[0:1], 0

; __device__ __forceinline__ void item_load(const Params& p, int it, f32x4 (&v)[8]) {
;     const int tid = otid(); WDesc d;
;     if (item_desc(p, it, d)) {
; #pragma unroll
;         for (int i = 0; i < 8; ++i) { const int idx = tid + i * 512, row = idx >> 6, c4 = idx & 63;
;             v[i] = __builtin_nontemporal_load((const f32x4*)(d.W + (size_t)(d.kb * 64 + row) * d.N + d.nb * 256 + c4 * 4)); }
;     } else {
;         const int R = it - PO_NORM, wid = tid >> 6, lane = tid & 63;
; #pragma unroll
;         for (int q = 0; q < 2; ++q)
; #pragma unroll
;             for (int i = 0; i < 4; ++i) v[q * 4 + i] = __builtin_nontemporal_load((const f32x4*)(p.x + ((size_t)R * 16 + wid * 2 + q) * DM + i * 256 + lane * 4));
;     }
; __device__ __forceinline__ void item_finish(const Params& p, int it, const f32x4 (&v)[8], LAS unsigned char* lds) {
;     ...
;         for (int i = 0; i < 4; ++i) { const int idx = tid + i * 512, col = idx >> 3, piece = idx & 7; float t[8];
; #pragma unroll
;             for (int k = 0; k < 8; ++k) t[k] = tile[(piece * 8 + k) * 257 + col];
;             u32x4 w4; w4.x = cvt_pk_bf16(t[0], t[1]); w4.y = cvt_pk_bf16(t[2], t[3]); w4.z = cvt_pk_bf16(t[4], t[5]); w4.w = cvt_pk_bf16(t[6], t[7]);
;             *(u32x4*)(d.Bt + (size_t)dest_row(d.kind, d.nb * 256 + col, d.NPART) * d.K + d.kb * 64 + piece * 8) = w4; }
;         __syncthreads();
;     } else {
;         const int R = it - PO_NORM, wid = tid >> 6, lane = tid & 63; bf16_t* AP = (bf16_t*)(p.ws + WS_AP);
; #pragma unroll
;         for (int q = 0; q < 2; ++q) { const int s = wid * 2 + q; float ss = 0.f;
; #pragma unroll
;             for (int i = 0; i < 4; ++i) { const f32x4 x = v[q * 4 + i]; ss += (x[0] * x[0] + x[1] * x[1]) + (x[2] * x[2] + x[3] * x[3]); }
; #pragma unroll
;             for (int o = 32; o >= 1; o >>= 1) ss += __shfl_xor(ss, o);
;             const float rs = rsqrtf(ss * (1.0f / DM) + RMS_EPS);
; #pragma unroll
;             for (int i = 0; i < 4; ++i) { const int c = i * 256 + lane * 4; const f32x4 gn = *(const f32x4*)(p.norm_mix + c); const f32x4 x = v[q * 4 + i];
;                 u32x2 w; w.x = cvt_pk_bf16(x[0] * rs * gn[0], x[1] * rs * gn[1]); w.y = cvt_pk_bf16(x[2] * rs * gn[2], x[3] * rs * gn[3]);
;                 *(u32x2*)(AP + ((size_t)(c >> 4) * NROW + R) * KA + s * 16 + (c & 15)) = w; } }
;     }
; }
.LBB0_346:
	global_load_dwordx4 v[62:65], v[30:31], off nt
	s_add_u32 s4, s94, 0xb00000
	s_addc_u32 s5, s95, 0
	s_add_u32 s6, s88, 0x1600000
	s_addc_u32 s7, s89, 0
	s_add_u32 s10, s62, 0x2d84000
	s_addc_u32 s11, s63, 0
	s_add_u32 s30, s62, 0x2584000
	v_readlane_b32 s36, v252, 6
	s_addc_u32 s31, s63, 0
	v_readlane_b32 s38, v252, 8
	v_readlane_b32 s39, v252, 9
	s_add_u32 s22, s38, 0x1000
	s_addc_u32 s23, s39, 0
	s_add_u32 s24, s62, 0x2004000
	s_addc_u32 s25, s63, 0
	s_add_u32 s26, s62, 0x1a84000
	s_addc_u32 s27, s63, 0
	s_add_u32 s64, s62, 0xf84000
	v_readlane_b32 s40, v252, 10
	s_addc_u32 s65, s63, 0
	v_readlane_b32 s41, v252, 11
	s_add_u32 s66, s40, 0x1000
	s_addc_u32 s67, s41, 0
	s_add_u32 s70, s62, 0x484000
	s_addc_u32 s71, s63, 0
	s_add_u32 s72, s62, 0x84000
	v_mbcnt_lo_u32_b32 v30, -1, 0
	s_addc_u32 s73, s63, 0
	s_mov_b32 s75, 0
	v_mov_b32_e32 v67, 0
	s_mov_b64 s[76:77], 0x1400
	s_mov_b64 s[78:79], 0x1800
	s_mov_b64 s[80:81], 0x1c00
	v_mov_b32_e32 v1, 0x358637bd
	s_mov_b32 s2, 0x800000
	s_movk_i32 s3, 0x300
	s_mov_b32 s8, 0xf800
	s_mov_b32 s9, 0x17800
	s_mov_b32 s12, 0x1f800
	s_movk_i32 s13, 0x404
	s_movk_i32 s14, 0x60
	v_mbcnt_hi_u32_b32 v72, -1, v30
	v_mov_b32_e32 v73, 0x8000
	v_mov_b32_e32 v74, 0x10000
	v_mov_b32_e32 v75, 0x18000
	v_readlane_b32 s37, v252, 7
	v_readlane_b32 s42, v252, 12
	v_readlane_b32 s43, v252, 13
	v_readlane_b32 s44, v252, 14
	v_readlane_b32 s45, v252, 15
	v_readlane_b32 s46, v252, 16
	v_readlane_b32 s47, v252, 17
	v_readlane_b32 s48, v252, 18
	v_readlane_b32 s49, v252, 19
	v_readlane_b32 s50, v252, 20
	v_readlane_b32 s51, v252, 21
	v_lshlrev_b32_e32 v122, 2, v232
	v_and_b32_e32 v122, 0xfc, v122
	v_lshlrev_b32_e32 v122, 2, v122
	global_load_dwordx4 v[106:109], v122, s[38:39]
	global_load_dwordx4 v[110:113], v122, s[38:39] offset:1024
	global_load_dwordx4 v[114:117], v122, s[38:39] offset:2048
	global_load_dwordx4 v[118:121], v122, s[38:39] offset:3072
	s_waitcnt vmcnt(0)
	s_branch .LBB0_349
.LBB0_347:
	v_ashrrev_i32_e32 v8, 31, v11
	v_mul_lo_u32 v10, s85, v11
	v_mul_lo_u32 v12, s84, v8
	v_mad_u64_u32 v[8:9], s[0:1], s84, v11, 0
	v_add3_u32 v9, v9, v12, v10
	v_lshl_add_u64 v[6:7], v[8:9], 1, v[6:7]
	global_store_dwordx4 v[6:7], v[2:5], off
	s_barrier
.LBB0_348:
	s_waitcnt vmcnt(0)
.Lprep2_copy:
	s_andn2_b64 vcc, exec, s[82:83]
	s_mov_b32 s33, s15
	v_mov_b32_e32 v26, v58
	v_mov_b32_e32 v27, v59
	v_mov_b32_e32 v28, v60
	v_mov_b32_e32 v29, v61
	v_mov_b32_e32 v22, v54
	v_mov_b32_e32 v23, v55
	v_mov_b32_e32 v24, v56
	v_mov_b32_e32 v25, v57
	v_mov_b32_e32 v18, v50
	v_mov_b32_e32 v19, v51
	v_mov_b32_e32 v20, v52
	v_mov_b32_e32 v21, v53
	v_mov_b32_e32 v14, v46
	v_mov_b32_e32 v15, v47
	v_mov_b32_e32 v16, v48
	v_mov_b32_e32 v17, v49
	v_mov_b32_e32 v10, v42
	v_mov_b32_e32 v11, v43
	v_mov_b32_e32 v12, v44
	v_mov_b32_e32 v13, v45
	v_mov_b32_e32 v6, v38
	v_mov_b32_e32 v7, v39
	v_mov_b32_e32 v8, v40
	v_mov_b32_e32 v9, v41
	v_mov_b32_e32 v2, v34
	v_mov_b32_e32 v3, v35
	v_mov_b32_e32 v4, v36
	v_mov_b32_e32 v5, v37
	v_mov_b32_e32 v62, v30
	v_mov_b32_e32 v63, v31
	v_mov_b32_e32 v64, v32
	v_mov_b32_e32 v65, v33
	s_cbranch_vccz .LBB0_453

; __device__ __forceinline__ void item_finish(const Params& p, int it, const f32x4 (&v)[8], LAS unsigned char* lds) {
;     ...
;         const int R = it - PO_NORM, wid = tid >> 6, lane = tid & 63; bf16_t* AP = (bf16_t*)(p.ws + WS_AP);
; #pragma unroll
;         for (int q = 0; q < 2; ++q) { const int s = wid * 2 + q; float ss = 0.f;
; #pragma unroll
;             for (int i = 0; i < 4; ++i) { const f32x4 x = v[q * 4 + i]; ss += (x[0] * x[0] + x[1] * x[1]) + (x[2] * x[2] + x[3] * x[3]); }
; #pragma unroll
;             for (int o = 32; o >= 1; o >>= 1) ss += __shfl_xor(ss, o);
;             const float rs = rsqrtf(ss * (1.0f / DM) + RMS_EPS);
.LBB0_379:
	v_mov_b32_e32 v68, v232
	s_mov_b64 s[0:1], -1
	s_cmpk_gt_i32 s33, 0x5df
	v_lshlrev_b32_e32 v69, 3, v68
	s_cbranch_scc0 .LBB0_381
	v_lshlrev_b32_e32 v66, 2, v68
	v_and_b32_e32 v90, 0xfc, v66
	v_readlane_b32 s36, v252, 6
	v_lshlrev_b32_e32 v98, 2, v90
	v_readlane_b32 s38, v252, 8
	v_readlane_b32 s39, v252, 9
	v_pk_mul_f32 v[70:71], v[24:25], v[24:25]
	v_pk_mul_f32 v[80:81], v[22:23], v[22:23]
	v_pk_mul_f32 v[82:83], v[28:29], v[28:29]
	v_pk_mul_f32 v[84:85], v[26:27], v[26:27]
	v_and_b32_e32 v87, 64, v72
	s_nop 0
	v_pk_mov_b32 v[88:89], v[84:85], v[82:83] op_sel:[1,0]
	v_mov_b32_e32 v85, v83
	v_pk_mov_b32 v[82:83], v[80:81], v[70:71] op_sel:[1,0]
	v_mov_b32_e32 v81, v71
	v_mul_f32_e32 v66, v18, v18
	v_mul_f32_e32 v86, v20, v20
	v_pk_add_f32 v[84:85], v[88:89], v[84:85]
	v_pk_add_f32 v[80:81], v[82:83], v[80:81]
	v_add_u32_e32 v92, 64, v87
	v_pk_fma_f32 v[70:71], v[18:19], v[18:19], v[66:67] op_sel_hi:[1,1,0]
	v_pk_fma_f32 v[86:87], v[20:21], v[20:21], v[86:87] op_sel_hi:[1,1,0]
	v_pk_add_f32 v[82:83], v[84:85], v[84:85] op_sel_hi:[0,1]
	v_pk_add_f32 v[80:81], v[80:81], v[80:81] op_sel_hi:[0,1]
	v_xor_b32_e32 v91, 32, v72
	v_mul_f32_e32 v70, v14, v14
	v_mul_f32_e32 v86, v15, v15
	v_mul_f32_e32 v82, v16, v16
	v_mul_f32_e32 v80, v17, v17
	v_cmp_lt_i32_e32 vcc, v91, v92
	v_pk_add_f32 v[70:71], v[70:71], v[86:87]
	v_pk_add_f32 v[80:81], v[82:83], v[80:81]
	v_cndmask_b32_e32 v66, v72, v91, vcc
	v_pk_add_f32 v[70:71], v[70:71], v[80:81]
	v_lshlrev_b32_e32 v99, 2, v66
	v_add_f32_e32 v66, v70, v71
	ds_bpermute_b32 v70, v99, v66
	v_xor_b32_e32 v71, 16, v72
	v_cmp_lt_i32_e32 vcc, v71, v92
	v_ashrrev_i32_e32 v82, 1, v68
	v_lshlrev_b32_e32 v86, 7, v90
	v_cndmask_b32_e32 v71, v72, v71, vcc
	v_lshlrev_b32_e32 v100, 2, v71
	s_waitcnt lgkmcnt(0)
	v_add_f32_e32 v66, v66, v70
	ds_bpermute_b32 v70, v100, v66
	v_xor_b32_e32 v71, 8, v72
	v_cmp_lt_i32_e32 vcc, v71, v92
	s_add_i32 s16, s33, 0xfffffa20
	v_mul_f32_e32 v94, v4, v4
	v_cndmask_b32_e32 v71, v72, v71, vcc
	v_lshlrev_b32_e32 v101, 2, v71
	s_waitcnt lgkmcnt(0)
	v_add_f32_e32 v66, v66, v70
	ds_bpermute_b32 v70, v101, v66
	v_xor_b32_e32 v71, 4, v72
	v_cmp_lt_i32_e32 vcc, v71, v92
	v_pk_fma_f32 v[94:95], v[4:5], v[4:5], v[94:95] op_sel_hi:[1,1,0]
	v_readlane_b32 s37, v252, 7
	v_cndmask_b32_e32 v71, v72, v71, vcc
	v_lshlrev_b32_e32 v102, 2, v71
	s_waitcnt lgkmcnt(0)
	v_add_f32_e32 v66, v66, v70
	ds_bpermute_b32 v70, v102, v66
	v_xor_b32_e32 v71, 2, v72
	v_cmp_lt_i32_e32 vcc, v71, v92
	v_mul_f32_e32 v94, v63, v63
	v_readlane_b32 s40, v252, 10
	v_cndmask_b32_e32 v71, v72, v71, vcc
	v_lshlrev_b32_e32 v103, 2, v71
	s_waitcnt lgkmcnt(0)
	v_add_f32_e32 v66, v66, v70
	ds_bpermute_b32 v70, v103, v66
	v_xor_b32_e32 v71, 1, v72
	v_cmp_lt_i32_e32 vcc, v71, v92
	v_pk_mul_f32 v[92:93], v[10:11], v[10:11]
	v_readlane_b32 s41, v252, 11
	v_cndmask_b32_e32 v71, v72, v71, vcc
	v_lshlrev_b32_e32 v104, 2, v71
	s_waitcnt lgkmcnt(0)
	v_add_f32_e32 v80, v66, v70
	ds_bpermute_b32 v81, v104, v80
	v_and_b32_e32 v66, 24, v69
	v_lshl_add_u64 v[70:71], s[96:97], 0, v[66:67]
	v_readlane_b32 s42, v252, 12
	v_readlane_b32 s43, v252, 13
	s_waitcnt lgkmcnt(0)
; __device__ __forceinline__ unsigned cvt_pk_bf16(float lo, float hi) { unsigned r; asm volatile("v_cvt_pk_bf16_f32 %0, %1, %2" : "=v"(r) : "v"(lo), "v"(hi)); return r; }
; __device__ __forceinline__ void item_finish(const Params& p, int it, const f32x4 (&v)[8], LAS unsigned char* lds) {
;     ...
;             const float rs = rsqrtf(ss * (1.0f / DM) + RMS_EPS);
; #pragma unroll
;             for (int i = 0; i < 4; ++i) { const int c = i * 256 + lane * 4; const f32x4 gn = *(const f32x4*)(p.norm_mix + c); const f32x4 x = v[q * 4 + i];
;                 u32x2 w; w.x = cvt_pk_bf16(x[0] * rs * gn[0], x[1] * rs * gn[1]); w.y = cvt_pk_bf16(x[2] * rs * gn[2], x[3] * rs * gn[3]);
;                 *(u32x2*)(AP + ((size_t)(c >> 4) * NROW + R) * KA + s * 16 + (c & 15)) = w; } }
	v_add_f32_e32 v66, v80, v81
	v_fmamk_f32 v66, v66, 0x3a800000, v1
	v_mul_f32_e32 v80, 0x4b800000, v66
	v_cmp_gt_f32_e32 vcc, s2, v66
	v_readlane_b32 s44, v252, 14
	v_readlane_b32 s45, v252, 15
	v_cndmask_b32_e32 v66, v66, v80, vcc
	v_rsq_f32_e32 v66, v66
	v_and_b32_e32 v80, 0xffffffe0, v82
	v_ashrrev_i32_e32 v81, 31, v80
	v_lshl_add_u64 v[70:71], v[80:81], 1, v[70:71]
	v_mul_f32_e32 v80, 0x45800000, v66
	v_cndmask_b32_e32 v66, v66, v80, vcc
	v_mul_f32_e32 v80, v26, v66
	v_mul_f32_e32 v81, v27, v66
	v_mul_f32_e32 v76, v106, v80
	v_mul_f32_e32 v77, v107, v81
	v_cvt_pk_bf16_f32 v76, v76, v77
	v_mul_f32_e32 v77, v28, v66
	v_mul_f32_e32 v77, v108, v77
	v_mul_f32_e32 v78, v29, v66
	v_mul_f32_e32 v78, v109, v78
	v_cvt_pk_bf16_f32 v77, v77, v78
	v_and_b32_e32 v78, 0x7800, v86
	v_add_u32_e32 v78, s16, v78
	v_mad_u64_u32 v[80:81], s[0:1], v78, s3, v[70:71]
	global_store_dwordx2 v[80:81], v[76:77], off
	s_nop 0
	v_bitop3_b32 v82, v86, s8, v73 bitop3:0xc8
	v_add_u32_e32 v82, s16, v82
	v_mul_f32_e32 v84, v22, v66
	v_mul_f32_e32 v85, v23, v66
	v_mad_u64_u32 v[82:83], s[0:1], v82, s3, v[70:71]
	v_mul_f32_e32 v87, v24, v66
	v_mul_f32_e32 v88, v25, v66
	v_mul_f32_e32 v89, v20, v66
	v_mul_f32_e32 v90, v21, v66
	v_readlane_b32 s46, v252, 16
	v_readlane_b32 s47, v252, 17
	v_readlane_b32 s48, v252, 18
	v_readlane_b32 s49, v252, 19
	v_readlane_b32 s50, v252, 20
	v_readlane_b32 s51, v252, 21
	v_mul_f32_e32 v76, v110, v84
	v_mul_f32_e32 v77, v111, v85
	v_mul_f32_e32 v78, v112, v87
	v_mul_f32_e32 v79, v113, v88
	v_cvt_pk_bf16_f32 v76, v76, v77
	v_cvt_pk_bf16_f32 v77, v78, v79
	global_store_dwordx2 v[82:83], v[76:77], off
	s_nop 0
	v_bitop3_b32 v84, v86, s9, v74 bitop3:0xc8
	v_add_u32_e32 v84, s16, v84
	v_mul_f32_e32 v87, v18, v66
	v_mul_f32_e32 v88, v19, v66
	v_mad_u64_u32 v[84:85], s[0:1], v84, s3, v[70:71]
	v_bitop3_b32 v86, v86, s12, v75 bitop3:0xc8
	v_add_u32_e32 v86, s16, v86
	v_mad_u64_u32 v[70:71], s[0:1], v86, s3, v[70:71]
	v_mul_f32_e32 v86, v14, v66
	s_mov_b64 s[0:1], 0
	v_mul_f32_e32 v76, v87, v114
	v_mul_f32_e32 v77, v88, v115
	v_mul_f32_e32 v78, v89, v116
	v_mul_f32_e32 v79, v90, v117
	v_cvt_pk_bf16_f32 v76, v76, v77
	v_cvt_pk_bf16_f32 v77, v78, v79
	global_store_dwordx2 v[84:85], v[76:77], off
	s_nop 0
	v_mul_f32_e32 v87, v15, v66
	v_mul_f32_e32 v88, v16, v66
	v_mul_f32_e32 v66, v17, v66
	v_pk_mul_f32 v[90:91], v[12:13], v[12:13]
	v_mul_f32_e32 v76, v86, v118
	v_mul_f32_e32 v77, v87, v119
	v_mul_f32_e32 v78, v88, v120
	v_mul_f32_e32 v66, v66, v121
	v_cvt_pk_bf16_f32 v76, v76, v77
	v_cvt_pk_bf16_f32 v77, v78, v66
	global_store_dwordx2 v[70:71], v[76:77], off
	s_nop 0
	v_pk_mul_f32 v[86:87], v[8:9], v[8:9]
	v_pk_mul_f32 v[88:89], v[6:7], v[6:7]
	v_pk_mov_b32 v[96:97], v[92:93], v[90:91] op_sel:[1,0]
	v_mov_b32_e32 v93, v91
	v_pk_mov_b32 v[90:91], v[88:89], v[86:87] op_sel:[1,0]
	v_mov_b32_e32 v89, v87
	v_mul_f32_e32 v66, v2, v2
	v_pk_add_f32 v[92:93], v[96:97], v[92:93]
	v_pk_add_f32 v[88:89], v[90:91], v[88:89]
	v_pk_fma_f32 v[86:87], v[2:3], v[2:3], v[66:67] op_sel_hi:[1,1,0]
	v_pk_add_f32 v[90:91], v[92:93], v[92:93] op_sel_hi:[0,1]
	v_pk_add_f32 v[88:89], v[88:89], v[88:89] op_sel_hi:[0,1]
	v_mul_f32_e32 v86, v62, v62
	v_mul_f32_e32 v90, v64, v64
	v_mul_f32_e32 v88, v65, v65
	v_pk_add_f32 v[86:87], v[86:87], v[94:95]
	v_pk_add_f32 v[88:89], v[90:91], v[88:89]
	s_nop 0
	v_pk_add_f32 v[86:87], v[86:87], v[88:89]
	s_nop 0
	v_add_f32_e32 v66, v86, v87
	ds_bpermute_b32 v86, v99, v66
	s_waitcnt lgkmcnt(0)
	v_add_f32_e32 v66, v66, v86
	ds_bpermute_b32 v86, v100, v66
	s_waitcnt lgkmcnt(0)
	v_add_f32_e32 v66, v66, v86
	ds_bpermute_b32 v86, v101, v66
	s_waitcnt lgkmcnt(0)
	v_add_f32_e32 v66, v66, v86
	ds_bpermute_b32 v86, v102, v66
	s_waitcnt lgkmcnt(0)
	v_add_f32_e32 v66, v66, v86
	ds_bpermute_b32 v86, v103, v66
	s_waitcnt lgkmcnt(0)
	v_add_f32_e32 v66, v66, v86
	ds_bpermute_b32 v86, v104, v66
	s_waitcnt lgkmcnt(0)
	v_add_f32_e32 v66, v66, v86
	v_fmamk_f32 v66, v66, 0x3a800000, v1
	v_mul_f32_e32 v86, 0x4b800000, v66
	v_cmp_gt_f32_e32 vcc, s2, v66
	s_nop 1
	v_cndmask_b32_e32 v66, v66, v86, vcc
	v_rsq_f32_e32 v66, v66
	s_nop 0
	v_mul_f32_e32 v86, 0x45800000, v66
	v_cndmask_b32_e32 v66, v66, v86, vcc
	v_mul_f32_e32 v86, v10, v66
	v_mul_f32_e32 v87, v11, v66
	v_mul_f32_e32 v88, v12, v66
	v_mul_f32_e32 v89, v13, v66
	v_mul_f32_e32 v76, v106, v86
	v_mul_f32_e32 v77, v107, v87
	v_mul_f32_e32 v78, v108, v88
	v_mul_f32_e32 v79, v109, v89
	v_cvt_pk_bf16_f32 v76, v76, v77
	v_cvt_pk_bf16_f32 v77, v78, v79
	global_store_dwordx2 v[80:81], v[76:77], off offset:32
	s_nop 0
	v_mul_f32_e32 v80, v6, v66
	v_mul_f32_e32 v81, v7, v66
	v_mul_f32_e32 v86, v8, v66
	v_mul_f32_e32 v87, v9, v66
	v_mul_f32_e32 v76, v110, v80
	v_mul_f32_e32 v77, v111, v81
	v_mul_f32_e32 v78, v112, v86
	v_mul_f32_e32 v79, v113, v87
	v_cvt_pk_bf16_f32 v76, v76, v77
	v_cvt_pk_bf16_f32 v77, v78, v79
	global_store_dwordx2 v[82:83], v[76:77], off offset:32
	s_nop 0
	v_mul_f32_e32 v80, v2, v66
	v_mul_f32_e32 v81, v3, v66
	v_mul_f32_e32 v82, v4, v66
	v_mul_f32_e32 v83, v5, v66
	v_mul_f32_e32 v76, v80, v114
	v_mul_f32_e32 v77, v81, v115
	v_mul_f32_e32 v78, v82, v116
	v_mul_f32_e32 v79, v83, v117
	v_cvt_pk_bf16_f32 v76, v76, v77
	v_cvt_pk_bf16_f32 v77, v78, v79
	global_store_dwordx2 v[84:85], v[76:77], off offset:32
	s_nop 0
	v_mul_f32_e32 v80, v62, v66
	v_mul_f32_e32 v81, v63, v66
	v_mul_f32_e32 v82, v64, v66
	v_mul_f32_e32 v66, v65, v66
	v_mul_f32_e32 v76, v80, v118
	v_mul_f32_e32 v77, v81, v119
	v_mul_f32_e32 v78, v82, v120
	v_mul_f32_e32 v66, v66, v121
	v_cvt_pk_bf16_f32 v76, v76, v77
	v_cvt_pk_bf16_f32 v77, v78, v66
	global_store_dwordx2 v[70:71], v[76:77], off offset:32
	s_waitcnt vmcnt(8)
	s_branch .Lprep2_copy
